# merge phase (P3): 64 bf16 pair packs per tile via v_cvt_pk_bf16_f32 instead of the integer RNE trick (-320 VALU per tile; phase is VALU-sensitive)
# baseline (speedup 1.0000x reference)
.LBB0_474:
	s_ashr_i32 s11, s10, 31
	v_lshl_add_u64 v[120:121], s[10:11], 1, v[66:67]
	v_lshl_add_u64 v[0:1], v[120:121], 0, v[34:35]
	global_load_dwordx4 v[0:3], v[0:1], off nt
	v_lshl_add_u64 v[108:109], v[120:121], 0, v[58:59]
	v_lshl_add_u64 v[112:113], v[120:121], 0, v[60:61]
	v_lshl_add_u64 v[4:5], v[120:121], 0, v[36:37]
	global_load_dwordx4 v[108:111], v[108:109], off nt
	v_lshl_add_u64 v[116:117], v[120:121], 0, v[62:63]
	global_load_dwordx4 v[112:115], v[112:113], off nt
	v_lshl_add_u64 v[8:9], v[120:121], 0, v[38:39]
	global_load_dwordx4 v[4:7], v[4:5], off nt
	v_lshl_add_u64 v[12:13], v[120:121], 0, v[40:41]
	global_load_dwordx4 v[116:119], v[116:117], off nt
	v_lshl_add_u64 v[16:17], v[120:121], 0, v[42:43]
	global_load_dwordx4 v[8:11], v[8:9], off nt
	v_lshl_add_u64 v[20:21], v[120:121], 0, v[44:45]
	v_lshl_add_u64 v[24:25], v[120:121], 0, v[46:47]
	v_lshl_add_u64 v[28:29], v[120:121], 0, v[48:49]
	v_lshl_add_u64 v[70:71], v[120:121], 0, v[50:51]
	v_lshl_add_u64 v[74:75], v[120:121], 0, v[52:53]
	v_lshl_add_u64 v[78:79], v[120:121], 0, v[54:55]
	v_lshl_add_u64 v[104:105], v[120:121], 0, v[56:57]
	v_lshl_add_u64 v[120:121], v[120:121], 0, v[64:65]
	global_load_dwordx4 v[120:123], v[120:121], off nt
	v_add_u32_e32 v124, v82, v83
	global_load_dwordx4 v[12:15], v[12:13], off nt
	v_add_u32_e32 v125, 0x2100, v32
	global_load_dwordx4 v[16:19], v[16:17], off nt
	v_add_u32_e32 v126, 0x2108, v32
	global_load_dwordx4 v[20:23], v[20:21], off nt
	v_add_u32_e32 v127, 0x4200, v32
	global_load_dwordx4 v[24:27], v[24:25], off nt
	v_add_u32_e32 v128, 0x4208, v32
	global_load_dwordx4 v[28:31], v[28:29], off nt
	v_add_u32_e32 v129, 0x6300, v32
	global_load_dwordx4 v[70:73], v[70:71], off nt
	v_add_u32_e32 v130, 0x6308, v32
	global_load_dwordx4 v[74:77], v[74:75], off nt
	v_add_u32_e32 v131, 0x8400, v32
	global_load_dwordx4 v[78:81], v[78:79], off nt
	v_add_u32_e32 v132, 0x8408, v32
	global_load_dwordx4 v[104:107], v[104:105], off nt
	v_add_u32_e32 v133, 0xa500, v32
	v_add_u32_e32 v134, 0xa508, v32
	v_add_u32_e32 v135, 0xc600, v32
	v_add_u32_e32 v136, 0xc608, v32
	v_add_u32_e32 v137, 0xe700, v32
	v_add_u32_e32 v138, 0xe708, v32
	v_add_u32_e32 v139, 0x2100, v124
	v_add_u32_e32 v140, 0x2108, v124
	v_add_u32_e32 v141, 0x4200, v124
	v_add_u32_e32 v142, 0x4208, v124
	v_add_u32_e32 v143, 0x6300, v124
	v_add_u32_e32 v144, 0x6308, v124
	v_add_u32_e32 v145, 0x8400, v124
	v_add_u32_e32 v146, 0x8408, v124
	v_add_u32_e32 v147, 0xa500, v124
	s_lshl_b64 s[0:1], s[10:11], 3
	s_add_u32 s0, s9, s0
	s_addc_u32 s1, s18, s1
	s_add_i32 s12, s8, s10
	s_ashr_i32 s13, s12, 31
	s_add_i32 s15, s15, s14
	s_add_i32 s10, s10, s19
	s_waitcnt vmcnt(15)
	ds_write2_b32 v124, v0, v1 offset1:1
	ds_write2_b32 v124, v2, v3 offset0:2 offset1:3
	s_waitcnt vmcnt(12)
	ds_write2_b32 v139, v4, v5 offset1:1
	ds_write2_b32 v140, v6, v7 offset1:1
	s_waitcnt vmcnt(10)
	ds_write2_b32 v141, v8, v9 offset1:1
	ds_write2_b32 v142, v10, v11 offset1:1
	s_waitcnt vmcnt(8)
	ds_write2_b32 v143, v12, v13 offset1:1
	ds_write2_b32 v144, v14, v15 offset1:1
	s_waitcnt vmcnt(7)
	ds_write2_b32 v145, v16, v17 offset1:1
	ds_write2_b32 v146, v18, v19 offset1:1
	s_waitcnt vmcnt(6)
	ds_write2_b32 v147, v20, v21 offset1:1
	ds_write2_b32 v32, v22, v23 offset0:2 offset1:3
	s_waitcnt vmcnt(5)
	ds_write2_b32 v125, v24, v25 offset1:1
	ds_write2_b32 v126, v26, v27 offset1:1
	s_waitcnt vmcnt(4)
	ds_write2_b32 v127, v28, v29 offset1:1
	ds_write2_b32 v128, v30, v31 offset1:1
	s_waitcnt vmcnt(3)
	ds_write2_b32 v129, v70, v71 offset1:1
	ds_write2_b32 v130, v72, v73 offset1:1
	s_waitcnt vmcnt(2)
	ds_write2_b32 v131, v74, v75 offset1:1
	ds_write2_b32 v132, v76, v77 offset1:1
	s_waitcnt vmcnt(1)
	ds_write2_b32 v133, v78, v79 offset1:1
	ds_write2_b32 v134, v80, v81 offset1:1
	s_waitcnt vmcnt(0)
	ds_write2_b32 v135, v104, v105 offset1:1
	ds_write2_b32 v136, v106, v107 offset1:1
	ds_write2_b32 v137, v108, v109 offset1:1
	ds_write2_b32 v138, v110, v111 offset1:1
	v_add_u32_e32 v0, 0xe700, v95
	ds_write2_b32 v0, v112, v113 offset1:1
	v_add_u32_e32 v0, 0xe708, v95
	ds_write2_b32 v0, v114, v115 offset1:1
	v_add_u32_e32 v0, 0xe700, v96
	ds_write2_b32 v0, v116, v117 offset1:1
	v_add_u32_e32 v0, 0xe708, v96
	ds_write2_b32 v0, v118, v119 offset1:1
	v_add_u32_e32 v0, 0xe700, v97
	ds_write2_b32 v0, v120, v121 offset1:1
	v_add_u32_e32 v0, 0xe708, v97
	ds_write2_b32 v0, v122, v123 offset1:1
	s_waitcnt lgkmcnt(0)
	s_barrier
	global_load_dwordx4 v[0:3], v33, s[0:1]
	global_load_dwordx4 v[4:7], v33, s[0:1] offset:16
	global_load_dwordx4 v[8:11], v33, s[0:1] offset:32
	global_load_dwordx4 v[12:15], v33, s[0:1] offset:48
	v_add_u32_e32 v26, s16, v86
	v_add_u32_e32 v30, s16, v87
	v_add_u32_e32 v123, 0xc68c, v84
	s_waitcnt vmcnt(3)
	v_ffbh_u32_e32 v16, v1
	v_ffbh_u32_e32 v17, v3
	s_waitcnt vmcnt(2)
	v_ffbh_u32_e32 v18, v5
	s_waitcnt vmcnt(1)
	v_ffbh_u32_e32 v20, v9
	v_min_u32_e32 v16, 32, v16
	v_min_u32_e32 v17, 32, v17
	v_min_u32_e32 v18, 32, v18
	v_min_u32_e32 v20, 32, v20
	v_lshlrev_b64 v[0:1], v16, v[0:1]
	v_lshlrev_b64 v[2:3], v17, v[2:3]
	v_lshlrev_b64 v[4:5], v18, v[4:5]
	v_lshlrev_b64 v[8:9], v20, v[8:9]
	v_ffbh_u32_e32 v21, v11
	v_min_u32_e32 v0, 1, v0
	v_min_u32_e32 v2, 1, v2
	v_min_u32_e32 v4, 1, v4
	v_min_u32_e32 v8, 1, v8
	v_min_u32_e32 v21, 32, v21
	v_or_b32_e32 v0, v1, v0
	v_or_b32_e32 v1, v3, v2
	v_or_b32_e32 v2, v5, v4
	v_or_b32_e32 v4, v9, v8
	v_ffbh_u32_e32 v19, v7
	s_waitcnt vmcnt(0)
	v_ffbh_u32_e32 v23, v15
	v_lshlrev_b64 v[10:11], v21, v[10:11]
	v_cvt_f32_u32_e32 v4, v4
	v_ffbh_u32_e32 v22, v13
	v_min_u32_e32 v19, 32, v19
	v_min_u32_e32 v23, 32, v23
	v_min_u32_e32 v10, 1, v10
	v_min_u32_e32 v22, 32, v22
	v_lshlrev_b64 v[6:7], v19, v[6:7]
	v_lshlrev_b64 v[14:15], v23, v[14:15]
	v_or_b32_e32 v5, v11, v10
	v_sub_u32_e32 v20, 32, v20
	v_lshlrev_b64 v[12:13], v22, v[12:13]
	v_min_u32_e32 v6, 1, v6
	v_min_u32_e32 v14, 1, v14
	v_cvt_f32_u32_e32 v5, v5
	v_min_u32_e32 v12, 1, v12
	v_or_b32_e32 v3, v7, v6
	v_or_b32_e32 v7, v15, v14
	v_ldexp_f32 v4, v4, v20
	v_or_b32_e32 v6, v13, v12
	v_cvt_f32_u32_e32 v0, v0
	v_cvt_f32_u32_e32 v1, v1
	v_cvt_f32_u32_e32 v2, v2
	v_cvt_f32_u32_e32 v3, v3
	v_mul_f32_e32 v107, 0x2f800000, v4
	v_cvt_f32_u32_e32 v4, v7
	v_sub_u32_e32 v21, 32, v21
	v_cvt_f32_u32_e32 v6, v6
	v_ldexp_f32 v5, v5, v21
	v_sub_u32_e32 v16, 32, v16
	v_sub_u32_e32 v17, 32, v17
	v_sub_u32_e32 v18, 32, v18
	v_sub_u32_e32 v19, 32, v19
	v_mul_f32_e32 v106, 0x2f800000, v5
	v_sub_u32_e32 v5, 32, v23
	v_sub_u32_e32 v22, 32, v22
	v_ldexp_f32 v0, v0, v16
	v_ldexp_f32 v1, v1, v17
	v_ldexp_f32 v2, v2, v18
	v_ldexp_f32 v3, v3, v19
	v_ldexp_f32 v4, v4, v5
	v_ldexp_f32 v6, v6, v22
	v_mul_f32_e32 v174, 0x2f800000, v0
	v_mul_f32_e32 v155, 0x2f800000, v1
	v_mul_f32_e32 v122, 0x2f800000, v2
	v_mul_f32_e32 v108, 0x2f800000, v3
	ds_read2_b64 v[0:3], v84 offset1:1
	ds_read2_b32 v[70:71], v84 offset0:33 offset1:34
	v_mul_f32_e32 v104, 0x2f800000, v4
	v_add_u32_e32 v4, 0x4200, v84
	v_add_u32_e32 v8, 0x4284, v84
	v_mul_f32_e32 v105, 0x2f800000, v6
	ds_read2_b64 v[4:7], v4 offset1:1
	ds_read2_b32 v[72:73], v8 offset1:1
	ds_read2_b32 v[74:75], v84 offset0:35 offset1:36
	v_add_u32_e32 v14, 0x8484, v84
	v_add_u32_e32 v8, 0x8400, v84
	ds_read2_b32 v[110:111], v14 offset1:1
	ds_read2_b32 v[116:117], v26 offset1:1
	ds_read2_b64 v[8:11], v8 offset1:1
	s_waitcnt lgkmcnt(6)
	v_lshlrev_b32_e32 v173, 16, v70
	s_waitcnt lgkmcnt(4)
	v_lshlrev_b32_e32 v202, 16, v72
	v_lshlrev_b32_e32 v172, 16, v0
	v_mul_f32_e32 v12, v173, v173
	v_lshlrev_b32_e32 v197, 16, v4
	v_mul_f32_e32 v13, v202, v202
	v_fmac_f32_e32 v12, v172, v172
	v_fmac_f32_e32 v13, v197, v197
	v_add_u32_e32 v18, 0xc684, v84
	v_add_u32_e32 v22, s16, v85
	v_add_f32_e32 v16, v12, v13
	v_add_u32_e32 v12, 0xc600, v84
	ds_read2_b32 v[112:113], v18 offset1:1
	ds_read2_b32 v[114:115], v22 offset1:1
	s_waitcnt lgkmcnt(4)
	v_lshlrev_b32_e32 v203, 16, v110
	ds_read2_b64 v[12:15], v12 offset1:1
	s_waitcnt lgkmcnt(3)
	v_lshlrev_b32_e32 v198, 16, v8
	v_mul_f32_e32 v17, v203, v203
	v_fmac_f32_e32 v17, v198, v198
	v_add_f32_e32 v20, v16, v17
	ds_read2_b64 v[16:19], v98 offset1:1
	ds_read2_b32 v[118:119], v30 offset1:1
	s_waitcnt lgkmcnt(4)
	v_lshlrev_b32_e32 v201, 16, v112
	s_waitcnt lgkmcnt(2)
	v_lshlrev_b32_e32 v199, 16, v12
	v_mul_f32_e32 v21, v201, v201
	v_lshlrev_b32_e32 v200, 16, v114
	v_fmac_f32_e32 v21, v199, v199
	s_waitcnt lgkmcnt(1)
	v_lshlrev_b32_e32 v195, 16, v16
	v_mul_f32_e32 v25, v200, v200
	v_add_f32_e32 v24, v20, v21
	ds_read2_b64 v[20:23], v99 offset1:1
	v_fmac_f32_e32 v25, v195, v195
	v_add_f32_e32 v28, v24, v25
	ds_read2_b64 v[24:27], v100 offset1:1
	v_and_b32_e32 v190, 0xffff0000, v70
	v_and_b32_e32 v188, 0xffff0000, v72
	v_and_b32_e32 v189, 0xffff0000, v0
	v_mul_f32_e32 v0, v190, v190
	v_and_b32_e32 v187, 0xffff0000, v4
	v_mul_f32_e32 v4, v188, v188
	v_lshlrev_b32_e32 v196, 16, v116
	v_fmac_f32_e32 v0, v189, v189
	v_fmac_f32_e32 v4, v187, v187
	v_and_b32_e32 v186, 0xffff0000, v110
	s_waitcnt lgkmcnt(1)
	v_lshlrev_b32_e32 v193, 16, v20
	v_mul_f32_e32 v29, v196, v196
	v_lshlrev_b32_e32 v194, 16, v118
	v_add_f32_e32 v0, v0, v4
	v_and_b32_e32 v185, 0xffff0000, v8
	v_mul_f32_e32 v4, v186, v186
	v_fmac_f32_e32 v29, v193, v193
	s_waitcnt lgkmcnt(0)
	v_lshlrev_b32_e32 v192, 16, v24
	v_mul_f32_e32 v77, v194, v194
	v_fmac_f32_e32 v4, v185, v185
	v_and_b32_e32 v184, 0xffff0000, v112
	v_add_f32_e32 v76, v28, v29
	v_fmac_f32_e32 v77, v192, v192
	v_add_f32_e32 v0, v0, v4
	v_and_b32_e32 v183, 0xffff0000, v12
	v_mul_f32_e32 v4, v184, v184
	v_add_f32_e32 v109, v76, v77
	v_add_u32_e32 v76, s16, v88
	v_fmac_f32_e32 v4, v183, v183
	v_and_b32_e32 v182, 0xffff0000, v114
	ds_read2_b64 v[28:31], v101 offset1:1
	ds_read2_b32 v[120:121], v76 offset1:1
	v_add_f32_e32 v0, v0, v4
	v_and_b32_e32 v181, 0xffff0000, v16
	v_mul_f32_e32 v4, v182, v182
	v_fmac_f32_e32 v4, v181, v181
	v_and_b32_e32 v180, 0xffff0000, v116
	v_add_f32_e32 v0, v0, v4
	v_and_b32_e32 v179, 0xffff0000, v20
	v_mul_f32_e32 v4, v180, v180
	v_fmac_f32_e32 v4, v179, v179
	v_and_b32_e32 v178, 0xffff0000, v118
	v_add_f32_e32 v0, v0, v4
	v_and_b32_e32 v177, 0xffff0000, v24
	v_mul_f32_e32 v4, v178, v178
	v_fmac_f32_e32 v4, v177, v177
	s_waitcnt lgkmcnt(0)
	v_and_b32_e32 v176, 0xffff0000, v120
	v_add_f32_e32 v0, v0, v4
	v_and_b32_e32 v175, 0xffff0000, v28
	v_mul_f32_e32 v4, v176, v176
	v_fmac_f32_e32 v4, v175, v175
	v_lshlrev_b32_e32 v171, 16, v71
	v_lshlrev_b32_e32 v169, 16, v73
	v_add_f32_e32 v210, v0, v4
	v_lshlrev_b32_e32 v170, 16, v1
	v_mul_f32_e32 v0, v171, v171
	v_lshlrev_b32_e32 v168, 16, v5
	v_mul_f32_e32 v4, v169, v169
	v_fmac_f32_e32 v0, v170, v170
	v_fmac_f32_e32 v4, v168, v168
	v_lshlrev_b32_e32 v167, 16, v111
	v_add_f32_e32 v0, v0, v4
	v_lshlrev_b32_e32 v166, 16, v9
	v_mul_f32_e32 v4, v167, v167
	v_fmac_f32_e32 v4, v166, v166
	v_lshlrev_b32_e32 v165, 16, v113
	v_add_f32_e32 v0, v0, v4
	v_lshlrev_b32_e32 v164, 16, v13
	v_mul_f32_e32 v4, v165, v165
	v_fmac_f32_e32 v4, v164, v164
	v_lshlrev_b32_e32 v163, 16, v115
	v_add_f32_e32 v0, v0, v4
	v_lshlrev_b32_e32 v162, 16, v17
	v_mul_f32_e32 v4, v163, v163
	v_fmac_f32_e32 v4, v162, v162
	v_lshlrev_b32_e32 v161, 16, v117
	v_add_f32_e32 v0, v0, v4
	v_lshlrev_b32_e32 v160, 16, v21
	v_mul_f32_e32 v4, v161, v161
	v_fmac_f32_e32 v4, v160, v160
	v_lshlrev_b32_e32 v159, 16, v119
	v_add_f32_e32 v0, v0, v4
	v_lshlrev_b32_e32 v158, 16, v25
	v_mul_f32_e32 v4, v159, v159
	v_fmac_f32_e32 v4, v158, v158
	v_lshlrev_b32_e32 v157, 16, v121
	v_add_f32_e32 v0, v0, v4
	v_lshlrev_b32_e32 v156, 16, v29
	v_mul_f32_e32 v4, v157, v157
	v_fmac_f32_e32 v4, v156, v156
	v_and_b32_e32 v154, 0xffff0000, v71
	v_and_b32_e32 v152, 0xffff0000, v73
	v_add_f32_e32 v211, v0, v4
	v_and_b32_e32 v153, 0xffff0000, v1
	v_mul_f32_e32 v0, v154, v154
	v_and_b32_e32 v151, 0xffff0000, v5
	v_mul_f32_e32 v1, v152, v152
	v_fmac_f32_e32 v0, v153, v153
	v_fmac_f32_e32 v1, v151, v151
	v_and_b32_e32 v150, 0xffff0000, v111
	v_add_f32_e32 v0, v0, v1
	v_and_b32_e32 v149, 0xffff0000, v9
	v_mul_f32_e32 v1, v150, v150
	v_fmac_f32_e32 v1, v149, v149
	v_and_b32_e32 v148, 0xffff0000, v113
	v_add_f32_e32 v0, v0, v1
	v_and_b32_e32 v147, 0xffff0000, v13
	v_mul_f32_e32 v1, v148, v148
	v_fmac_f32_e32 v1, v147, v147
	v_and_b32_e32 v146, 0xffff0000, v115
	v_add_f32_e32 v0, v0, v1
	v_and_b32_e32 v145, 0xffff0000, v17
	v_mul_f32_e32 v1, v146, v146
	v_fmac_f32_e32 v1, v145, v145
	v_and_b32_e32 v144, 0xffff0000, v117
	v_add_f32_e32 v0, v0, v1
	v_and_b32_e32 v143, 0xffff0000, v21
	v_mul_f32_e32 v1, v144, v144
	v_add_u32_e32 v76, 0x428c, v84
	v_add_u32_e32 v77, 0x848c, v84
	v_fmac_f32_e32 v1, v143, v143
	v_and_b32_e32 v142, 0xffff0000, v119
	ds_read2_b32 v[80:81], v76 offset1:1
	ds_read2_b32 v[78:79], v77 offset1:1
	ds_read2_b32 v[76:77], v123 offset1:1
	v_add_f32_e32 v0, v0, v1
	v_and_b32_e32 v141, 0xffff0000, v25
	v_mul_f32_e32 v1, v142, v142
	v_fmac_f32_e32 v1, v141, v141
	v_and_b32_e32 v140, 0xffff0000, v121
	v_add_f32_e32 v0, v0, v1
	v_and_b32_e32 v139, 0xffff0000, v29
	v_mul_f32_e32 v1, v140, v140
	v_fmac_f32_e32 v1, v139, v139
	v_lshlrev_b32_e32 v133, 16, v74
	s_waitcnt lgkmcnt(2)
	v_lshlrev_b32_e32 v131, 16, v80
	v_add_f32_e32 v212, v0, v1
	v_lshlrev_b32_e32 v132, 16, v2
	v_mul_f32_e32 v0, v133, v133
	v_lshlrev_b32_e32 v130, 16, v6
	v_mul_f32_e32 v1, v131, v131
	v_fmac_f32_e32 v0, v132, v132
	v_fmac_f32_e32 v1, v130, v130
	s_waitcnt lgkmcnt(1)
	v_lshlrev_b32_e32 v129, 16, v78
	v_add_f32_e32 v0, v0, v1
	v_lshlrev_b32_e32 v128, 16, v10
	v_mul_f32_e32 v1, v129, v129
	v_fmac_f32_e32 v1, v128, v128
	s_waitcnt lgkmcnt(0)
	v_lshlrev_b32_e32 v127, 16, v76
	v_add_f32_e32 v0, v0, v1
	v_lshlrev_b32_e32 v126, 16, v14
	v_mul_f32_e32 v1, v127, v127
	v_fmac_f32_e32 v1, v126, v126
	v_add_f32_e32 v8, v0, v1
	v_add_u32_e32 v0, s17, v85
	ds_read2_b32 v[0:1], v0 offset1:1
	v_and_b32_e32 v121, 0xffff0000, v74
	v_and_b32_e32 v119, 0xffff0000, v80
	v_lshlrev_b32_e32 v204, 16, v120
	v_and_b32_e32 v120, 0xffff0000, v2
	v_mul_f32_e32 v2, v121, v121
	v_and_b32_e32 v118, 0xffff0000, v6
	v_mul_f32_e32 v6, v119, v119
	v_fmac_f32_e32 v2, v120, v120
	v_fmac_f32_e32 v6, v118, v118
	v_and_b32_e32 v117, 0xffff0000, v78
	v_add_u32_e32 v4, s17, v86
	v_add_f32_e32 v2, v2, v6
	v_and_b32_e32 v116, 0xffff0000, v10
	v_mul_f32_e32 v6, v117, v117
	v_add_u32_e32 v9, s17, v87
	v_add_u32_e32 v12, s17, v88
	ds_read2_b32 v[4:5], v4 offset1:1
	ds_read2_b32 v[206:207], v9 offset1:1
	ds_read2_b32 v[208:209], v12 offset1:1
	v_fmac_f32_e32 v6, v116, v116
	v_and_b32_e32 v115, 0xffff0000, v76
	v_add_f32_e32 v2, v2, v6
	v_and_b32_e32 v114, 0xffff0000, v14
	v_mul_f32_e32 v6, v115, v115
	s_waitcnt lgkmcnt(3)
	v_and_b32_e32 v113, 0xffff0000, v0
	v_lshlrev_b32_e32 v138, 16, v0
	v_fmac_f32_e32 v6, v114, v114
	v_and_b32_e32 v112, 0xffff0000, v18
	v_mul_f32_e32 v0, v113, v113
	v_lshlrev_b32_e32 v191, 16, v28
	v_mul_f32_e32 v123, v204, v204
	v_add_f32_e32 v2, v2, v6
	v_fmac_f32_e32 v0, v112, v112
	s_waitcnt lgkmcnt(2)
	v_and_b32_e32 v111, 0xffff0000, v4
	v_fmac_f32_e32 v123, v191, v191
	v_add_f32_e32 v0, v2, v0
	v_and_b32_e32 v110, 0xffff0000, v22
	v_mul_f32_e32 v2, v111, v111
	v_add_f32_e32 v205, v109, v123
	v_fmac_f32_e32 v2, v110, v110
	s_waitcnt lgkmcnt(1)
	v_and_b32_e32 v109, 0xffff0000, v206
	v_add_f32_e32 v0, v0, v2
	v_and_b32_e32 v80, 0xffff0000, v26
	v_mul_f32_e32 v2, v109, v109
	v_fmac_f32_e32 v2, v80, v80
	s_waitcnt lgkmcnt(0)
	v_and_b32_e32 v78, 0xffff0000, v208
	v_add_f32_e32 v0, v0, v2
	v_and_b32_e32 v76, 0xffff0000, v30
	v_mul_f32_e32 v2, v78, v78
	v_fmac_f32_e32 v2, v76, v76
	v_lshlrev_b32_e32 v74, 16, v75
	v_lshlrev_b32_e32 v72, 16, v81
	v_lshlrev_b32_e32 v135, 16, v206
	v_add_f32_e32 v206, v0, v2
	v_lshlrev_b32_e32 v73, 16, v3
	v_mul_f32_e32 v0, v74, v74
	v_lshlrev_b32_e32 v71, 16, v7
	v_mul_f32_e32 v2, v72, v72
	v_fmac_f32_e32 v0, v73, v73
	v_fmac_f32_e32 v2, v71, v71
	v_lshlrev_b32_e32 v70, 16, v79
	v_lshlrev_b32_e32 v124, 16, v30
	v_add_f32_e32 v0, v0, v2
	v_lshlrev_b32_e32 v30, 16, v11
	v_mul_f32_e32 v2, v70, v70
	v_fmac_f32_e32 v2, v30, v30
	v_lshlrev_b32_e32 v29, 16, v77
	v_add_f32_e32 v0, v0, v2
	v_lshlrev_b32_e32 v28, 16, v15
	v_mul_f32_e32 v2, v29, v29
	v_lshlrev_b32_e32 v134, 16, v26
	v_fmac_f32_e32 v2, v28, v28
	v_lshlrev_b32_e32 v26, 16, v1
	v_add_f32_e32 v0, v0, v2
	v_lshlrev_b32_e32 v25, 16, v19
	v_mul_f32_e32 v2, v26, v26
	v_fmac_f32_e32 v2, v25, v25
	v_lshlrev_b32_e32 v24, 16, v5
	v_lshlrev_b32_e32 v136, 16, v22
	v_add_f32_e32 v0, v0, v2
	v_lshlrev_b32_e32 v22, 16, v23
	v_mul_f32_e32 v2, v24, v24
	v_lshlrev_b32_e32 v123, 16, v18
	v_mul_f32_e32 v9, v138, v138
	v_fmac_f32_e32 v2, v22, v22
	v_lshlrev_b32_e32 v21, 16, v207
	v_fmac_f32_e32 v9, v123, v123
	v_lshlrev_b32_e32 v137, 16, v4
	v_add_f32_e32 v0, v0, v2
	v_lshlrev_b32_e32 v20, 16, v27
	v_mul_f32_e32 v2, v21, v21
	v_add_f32_e32 v8, v8, v9
	v_mul_f32_e32 v9, v137, v137
	v_fmac_f32_e32 v2, v20, v20
	v_lshlrev_b32_e32 v18, 16, v209
	v_fmac_f32_e32 v9, v136, v136
	v_add_f32_e32 v0, v0, v2
	v_lshlrev_b32_e32 v17, 16, v31
	v_mul_f32_e32 v2, v18, v18
	v_add_f32_e32 v8, v8, v9
	v_mul_f32_e32 v9, v135, v135
	v_fmac_f32_e32 v2, v17, v17
	v_and_b32_e32 v16, 0xffff0000, v75
	v_and_b32_e32 v13, 0xffff0000, v81
	v_fmac_f32_e32 v9, v134, v134
	v_lshlrev_b32_e32 v125, 16, v208
	v_add_f32_e32 v208, v0, v2
	v_and_b32_e32 v14, 0xffff0000, v3
	v_mul_f32_e32 v0, v16, v16
	v_and_b32_e32 v12, 0xffff0000, v7
	v_mul_f32_e32 v2, v13, v13
	v_add_f32_e32 v8, v8, v9
	v_mul_f32_e32 v9, v125, v125
	v_fmac_f32_e32 v0, v14, v14
	v_fmac_f32_e32 v2, v12, v12
	v_and_b32_e32 v10, 0xffff0000, v11
	v_and_b32_e32 v11, 0xffff0000, v79
	v_fmac_f32_e32 v9, v124, v124
	v_add_f32_e32 v0, v0, v2
	v_mul_f32_e32 v2, v11, v11
	v_add_f32_e32 v213, v8, v9
	v_fmac_f32_e32 v2, v10, v10
	v_and_b32_e32 v9, 0xffff0000, v77
	v_add_f32_e32 v0, v0, v2
	v_and_b32_e32 v8, 0xffff0000, v15
	v_mul_f32_e32 v2, v9, v9
	v_and_b32_e32 v7, 0xffff0000, v1
	v_fmac_f32_e32 v2, v8, v8
	v_and_b32_e32 v6, 0xffff0000, v19
	v_mul_f32_e32 v1, v7, v7
	v_add_f32_e32 v0, v0, v2
	v_fmac_f32_e32 v1, v6, v6
	v_and_b32_e32 v5, 0xffff0000, v5
	v_add_f32_e32 v0, v0, v1
	v_and_b32_e32 v4, 0xffff0000, v23
	v_mul_f32_e32 v1, v5, v5
	v_fmac_f32_e32 v1, v4, v4
	v_and_b32_e32 v3, 0xffff0000, v207
	v_add_f32_e32 v0, v0, v1
	v_and_b32_e32 v2, 0xffff0000, v27
	v_mul_f32_e32 v1, v3, v3
	v_fmac_f32_e32 v1, v2, v2
	v_add_f32_e32 v15, v0, v1
	v_and_b32_e32 v0, 0xffff0000, v31
	ds_bpermute_b32 v23, v89, v205
	ds_bpermute_b32 v27, v89, v210
	ds_bpermute_b32 v31, v89, v211
	v_and_b32_e32 v1, 0xffff0000, v209
	ds_bpermute_b32 v77, v89, v206
	v_mul_f32_e32 v19, v1, v1
	v_fmac_f32_e32 v19, v0, v0
	ds_bpermute_b32 v75, v89, v213
	v_add_f32_e32 v15, v15, v19
	ds_bpermute_b32 v79, v89, v208
	s_waitcnt lgkmcnt(5)
	v_add_f32_e32 v19, v205, v23
	s_waitcnt lgkmcnt(4)
	v_add_f32_e32 v23, v210, v27
	s_waitcnt lgkmcnt(3)
	v_add_f32_e32 v27, v211, v31
	ds_bpermute_b32 v81, v89, v15
	ds_bpermute_b32 v31, v89, v212
	s_waitcnt lgkmcnt(4)
	v_add_f32_e32 v77, v206, v77
	ds_bpermute_b32 v206, v90, v27
	s_waitcnt lgkmcnt(4)
	v_add_f32_e32 v75, v213, v75
	ds_bpermute_b32 v205, v90, v23
	s_waitcnt lgkmcnt(4)
	v_add_f32_e32 v79, v208, v79
	ds_bpermute_b32 v208, v90, v75
	s_waitcnt lgkmcnt(4)
	v_add_f32_e32 v15, v15, v81
	s_waitcnt lgkmcnt(3)
	v_add_f32_e32 v31, v212, v31
	ds_bpermute_b32 v81, v90, v19
	s_waitcnt lgkmcnt(3)
	v_add_f32_e32 v27, v27, v206
	ds_bpermute_b32 v206, v90, v15
	ds_bpermute_b32 v207, v90, v31
	s_waitcnt lgkmcnt(4)
	v_add_f32_e32 v23, v23, v205
	ds_bpermute_b32 v205, v90, v79
	s_waitcnt lgkmcnt(4)
	v_add_f32_e32 v75, v75, v208
	ds_bpermute_b32 v208, v91, v23
	s_waitcnt lgkmcnt(4)
	v_add_f32_e32 v19, v19, v81
	ds_bpermute_b32 v81, v90, v77
	s_waitcnt lgkmcnt(4)
	v_add_f32_e32 v15, v15, v206
	ds_bpermute_b32 v206, v91, v75
	s_waitcnt lgkmcnt(4)
	v_add_f32_e32 v31, v31, v207
	ds_bpermute_b32 v207, v91, v19
	s_waitcnt lgkmcnt(4)
	v_add_f32_e32 v79, v79, v205
	ds_bpermute_b32 v205, v91, v31
	s_waitcnt lgkmcnt(4)
	v_add_f32_e32 v23, v23, v208
	ds_bpermute_b32 v208, v91, v79
	s_waitcnt lgkmcnt(4)
	v_add_f32_e32 v77, v77, v81
	ds_bpermute_b32 v81, v91, v27
	s_waitcnt lgkmcnt(4)
	v_add_f32_e32 v75, v75, v206
	ds_bpermute_b32 v206, v92, v23
	s_waitcnt lgkmcnt(4)
	v_add_f32_e32 v19, v19, v207
	ds_bpermute_b32 v207, v91, v77
	s_waitcnt lgkmcnt(4)
	v_add_f32_e32 v31, v31, v205
	ds_bpermute_b32 v205, v92, v19
	s_waitcnt lgkmcnt(4)
	v_add_f32_e32 v79, v79, v208
	ds_bpermute_b32 v208, v92, v31
	s_waitcnt lgkmcnt(4)
	v_add_f32_e32 v27, v27, v81
	s_waitcnt lgkmcnt(3)
	v_add_f32_e32 v23, v23, v206
	ds_bpermute_b32 v206, v92, v79
	s_waitcnt lgkmcnt(3)
	v_add_f32_e32 v77, v77, v207
	ds_bpermute_b32 v81, v91, v15
	ds_bpermute_b32 v207, v92, v27
	s_waitcnt lgkmcnt(4)
	v_add_f32_e32 v19, v19, v205
	ds_bpermute_b32 v205, v92, v77
	s_waitcnt lgkmcnt(4)
	v_add_f32_e32 v31, v31, v208
	ds_bpermute_b32 v208, v93, v19
	s_waitcnt lgkmcnt(4)
	v_add_f32_e32 v79, v79, v206
	ds_bpermute_b32 v206, v93, v31
	s_waitcnt lgkmcnt(4)
	v_add_f32_e32 v15, v15, v81
	s_waitcnt lgkmcnt(3)
	v_add_f32_e32 v27, v27, v207
	ds_bpermute_b32 v81, v92, v75
	ds_bpermute_b32 v207, v92, v15
	s_waitcnt lgkmcnt(4)
	v_add_f32_e32 v77, v77, v205
	ds_bpermute_b32 v205, v93, v27
	s_waitcnt lgkmcnt(4)
	v_add_f32_e32 v19, v19, v208
	ds_bpermute_b32 v208, v93, v77
	s_waitcnt lgkmcnt(4)
	v_add_f32_e32 v31, v31, v206
	ds_bpermute_b32 v206, v94, v19
	s_waitcnt lgkmcnt(4)
	v_add_f32_e32 v75, v75, v81
	s_waitcnt lgkmcnt(3)
	v_add_f32_e32 v15, v15, v207
	ds_bpermute_b32 v207, v93, v75
	s_waitcnt lgkmcnt(3)
	v_add_f32_e32 v27, v27, v205
	ds_bpermute_b32 v81, v93, v23
	s_waitcnt lgkmcnt(3)
	v_add_f32_e32 v77, v77, v208
	ds_bpermute_b32 v205, v93, v15
	ds_bpermute_b32 v208, v94, v27
	s_waitcnt lgkmcnt(4)
	v_add_f32_e32 v19, v19, v206
	v_fmamk_f32 v19, v19, 0x3a800000, v102
	s_waitcnt lgkmcnt(3)
	v_add_f32_e32 v75, v75, v207
	v_mul_f32_e32 v206, 0x4f800000, v19
	v_cmp_gt_f32_e32 vcc, s23, v19
	s_waitcnt lgkmcnt(2)
	v_add_f32_e32 v23, v23, v81
	s_waitcnt lgkmcnt(1)
	v_add_f32_e32 v15, v15, v205
	s_waitcnt lgkmcnt(0)
	v_add_f32_e32 v205, v27, v208
	ds_bpermute_b32 v27, v94, v75
	v_cndmask_b32_e32 v19, v19, v206, vcc
	ds_bpermute_b32 v81, v93, v79
	ds_bpermute_b32 v207, v94, v23
	v_sqrt_f32_e32 v206, v19
	s_waitcnt lgkmcnt(2)
	v_add_f32_e32 v27, v75, v27
	v_fmamk_f32 v174, v174, 0x3a800000, v102
	s_waitcnt lgkmcnt(1)
	v_add_f32_e32 v79, v79, v81
	v_add_u32_e32 v75, -1, v206
	s_waitcnt lgkmcnt(0)
	v_add_f32_e32 v81, v23, v207
	v_fma_f32 v207, -v75, v206, v19
	v_cmp_ge_f32_e64 s[4:5], 0, v207
	v_add_u32_e32 v207, 1, v206
	v_mul_f32_e32 v210, 0x4f800000, v174
	v_cndmask_b32_e64 v75, v206, v75, s[4:5]
	v_fma_f32 v206, -v207, v206, v19
	v_cmp_lt_f32_e64 s[4:5], 0, v206
	ds_bpermute_b32 v23, v94, v31
	v_fmamk_f32 v155, v155, 0x3a800000, v102
	v_cndmask_b32_e64 v75, v75, v207, s[4:5]
	v_mul_f32_e32 v206, 0x37800000, v75
	v_cndmask_b32_e32 v75, v75, v206, vcc
	v_cmp_class_f32_e32 vcc, v19, v103
	v_cmp_gt_f32_e64 s[4:5], s23, v174
	s_waitcnt lgkmcnt(0)
	v_add_f32_e32 v31, v31, v23
	v_cndmask_b32_e32 v19, v75, v19, vcc
	v_div_scale_f32 v75, s[0:1], v19, v19, 1.0
	v_rcp_f32_e32 v206, v75
	v_cndmask_b32_e64 v174, v174, v210, s[4:5]
	v_sqrt_f32_e32 v210, v174
	ds_bpermute_b32 v23, v94, v77
	v_fma_f32 v208, -v75, v206, 1.0
	v_fmac_f32_e32 v206, v208, v206
	v_div_scale_f32 v208, vcc, 1.0, v19, 1.0
	v_mul_f32_e32 v209, v208, v206
	v_fma_f32 v211, -v75, v209, v208
	v_fmac_f32_e32 v209, v211, v206
	v_fma_f32 v75, -v75, v209, v208
	v_add_u32_e32 v208, -1, v210
	v_fma_f32 v211, -v208, v210, v174
	v_cmp_ge_f32_e64 s[6:7], 0, v211
	v_add_u32_e32 v211, 1, v210
	v_div_fmas_f32 v75, v75, v206, v209
	v_cndmask_b32_e64 v208, v210, v208, s[6:7]
	v_fma_f32 v210, -v211, v210, v174
	v_cmp_lt_f32_e64 s[6:7], 0, v210
	v_div_fixup_f32 v75, v75, v19, 1.0
	s_waitcnt lgkmcnt(0)
	v_add_f32_e32 v23, v77, v23
	v_cndmask_b32_e64 v208, v208, v211, s[6:7]
	v_mul_f32_e32 v210, 0x37800000, v208
	v_cndmask_b32_e64 v208, v208, v210, s[4:5]
	v_cmp_class_f32_e64 s[4:5], v174, v103
	ds_bpermute_b32 v77, v94, v79
	ds_bpermute_b32 v207, v94, v15
	v_cndmask_b32_e64 v174, v208, v174, s[4:5]
	v_div_scale_f32 v208, s[0:1], v174, v174, 1.0
	v_rcp_f32_e32 v210, v208
	s_waitcnt lgkmcnt(0)
	v_add_f32_e32 v15, v15, v207
	v_fmamk_f32 v122, v122, 0x3a800000, v102
	v_fmamk_f32 v31, v31, 0x3a800000, v102
	v_fma_f32 v19, -v208, v210, 1.0
	v_fmac_f32_e32 v210, v19, v210
	v_div_scale_f32 v19, vcc, 1.0, v174, 1.0
	v_mul_f32_e32 v206, v19, v210
	v_fma_f32 v209, -v208, v206, v19
	v_fmac_f32_e32 v206, v209, v210
	v_fma_f32 v19, -v208, v206, v19
	v_div_fmas_f32 v19, v19, v210, v206
	v_div_fixup_f32 v174, v19, v174, 1.0
	v_div_scale_f32 v206, s[0:1], v174, v174, v75
	v_rcp_f32_e32 v208, v206
	v_add_f32_e32 v19, v79, v77
	s_lshl_b64 s[0:1], s[12:13], 12
	v_fmamk_f32 v108, v108, 0x3a800000, v102
	v_fma_f32 v77, -v206, v208, 1.0
	v_fmac_f32_e32 v208, v77, v208
	v_div_scale_f32 v77, vcc, v75, v174, v75
	v_mul_f32_e32 v79, v77, v208
	v_fma_f32 v207, -v206, v79, v77
	v_fmac_f32_e32 v79, v207, v208
	v_fma_f32 v77, -v206, v79, v77
	v_div_fmas_f32 v77, v77, v208, v79
	v_div_fixup_f32 v75, v77, v174, v75
	v_mul_f32_e32 v77, v75, v172
	v_mul_f32_e32 v79, v75, v173
	v_lshl_add_u64 v[206:207], v[68:69], 0, s[0:1]
	v_cvt_pk_bf16_f32 v77, v77, v79
	global_store_dword v[206:207], v77, off offset:2048
	v_mul_f32_e32 v77, v75, v197
	v_mul_f32_e32 v79, v75, v202
	v_cvt_pk_bf16_f32 v77, v77, v79
	global_store_dword v[206:207], v77, off offset:2304
	v_mul_f32_e32 v77, v75, v198
	v_mul_f32_e32 v79, v75, v203
	v_cvt_pk_bf16_f32 v77, v77, v79
	global_store_dword v[206:207], v77, off offset:2560
	v_mul_f32_e32 v77, v75, v199
	v_mul_f32_e32 v79, v75, v201
	v_cvt_pk_bf16_f32 v77, v77, v79
	global_store_dword v[206:207], v77, off offset:2816
	v_mul_f32_e32 v77, v75, v195
	v_mul_f32_e32 v79, v75, v200
	v_cvt_pk_bf16_f32 v77, v77, v79
	global_store_dword v[206:207], v77, off offset:3072
	v_mul_f32_e32 v77, v75, v193
	v_mul_f32_e32 v79, v75, v196
	v_cvt_pk_bf16_f32 v77, v77, v79
	global_store_dword v[206:207], v77, off offset:3328
	v_mul_f32_e32 v77, v75, v192
	v_mul_f32_e32 v79, v75, v194
	v_cvt_pk_bf16_f32 v77, v77, v79
	global_store_dword v[206:207], v77, off offset:3584
	v_fmamk_f32 v77, v81, 0x3a800000, v102
	v_mul_f32_e32 v79, 0x4f800000, v77
	v_cmp_gt_f32_e32 vcc, s23, v77
	v_mul_f32_e32 v192, 0x4f800000, v155
	v_mul_f32_e32 v81, v75, v191
	v_cndmask_b32_e32 v77, v77, v79, vcc
	v_sqrt_f32_e32 v79, v77
	v_mul_f32_e32 v75, v75, v204
	v_add_u32_e32 v173, -1, v79
	v_fma_f32 v174, -v173, v79, v77
	v_cmp_ge_f32_e64 s[4:5], 0, v174
	v_add_u32_e32 v174, 1, v79
	s_nop 0
	v_cndmask_b32_e64 v173, v79, v173, s[4:5]
	v_fma_f32 v79, -v174, v79, v77
	v_cmp_lt_f32_e64 s[4:5], 0, v79
	s_nop 1
	v_cndmask_b32_e64 v79, v173, v174, s[4:5]
	v_mul_f32_e32 v173, 0x37800000, v79
	v_cndmask_b32_e32 v79, v79, v173, vcc
	v_cmp_class_f32_e32 vcc, v77, v103
	v_cmp_gt_f32_e64 s[4:5], s23, v155
	v_cvt_pk_bf16_f32 v75, v81, v75
	v_cndmask_b32_e32 v77, v79, v77, vcc
	v_div_scale_f32 v79, s[0:1], v77, v77, 1.0
	v_rcp_f32_e32 v173, v79
	v_cndmask_b32_e64 v155, v155, v192, s[4:5]
	v_sqrt_f32_e32 v192, v155
	global_store_dword v[206:207], v75, off offset:3840
	v_fma_f32 v174, -v79, v173, 1.0
	v_fmac_f32_e32 v173, v174, v173
	v_div_scale_f32 v174, vcc, 1.0, v77, 1.0
	v_mul_f32_e32 v191, v174, v173
	v_fma_f32 v193, -v79, v191, v174
	v_fmac_f32_e32 v191, v193, v173
	v_fma_f32 v79, -v79, v191, v174
	v_add_u32_e32 v174, -1, v192
	v_fma_f32 v193, -v174, v192, v155
	v_cmp_ge_f32_e64 s[6:7], 0, v193
	v_add_u32_e32 v193, 1, v192
	v_div_fmas_f32 v79, v79, v173, v191
	v_cndmask_b32_e64 v174, v192, v174, s[6:7]
	v_fma_f32 v192, -v193, v192, v155
	v_cmp_lt_f32_e64 s[6:7], 0, v192
	v_div_fixup_f32 v77, v79, v77, 1.0
	v_fmamk_f32 v27, v27, 0x3a800000, v102
	v_cndmask_b32_e64 v174, v174, v193, s[6:7]
	v_mul_f32_e32 v192, 0x37800000, v174
	v_cndmask_b32_e64 v174, v174, v192, s[4:5]
	v_cmp_class_f32_e64 s[4:5], v155, v103
	v_fmamk_f32 v107, v107, 0x3a800000, v102
	v_fmamk_f32 v23, v23, 0x3a800000, v102
	v_cndmask_b32_e64 v155, v174, v155, s[4:5]
	v_div_scale_f32 v174, s[0:1], v155, v155, 1.0
	v_rcp_f32_e32 v192, v174
	v_fmamk_f32 v106, v106, 0x3a800000, v102
	v_fmamk_f32 v19, v19, 0x3a800000, v102
	v_fmamk_f32 v15, v15, 0x3a800000, v102
	v_fma_f32 v79, -v174, v192, 1.0
	v_fmac_f32_e32 v192, v79, v192
	v_div_scale_f32 v79, vcc, 1.0, v155, 1.0
	v_mul_f32_e32 v173, v79, v192
	v_fma_f32 v191, -v174, v173, v79
	v_fmac_f32_e32 v173, v191, v192
	v_fma_f32 v79, -v174, v173, v79
	v_div_fmas_f32 v79, v79, v192, v173
	v_div_fixup_f32 v79, v79, v155, 1.0
	v_div_scale_f32 v155, s[0:1], v79, v79, v77
	v_rcp_f32_e32 v173, v155
	s_add_i32 s0, s12, 1
	s_ashr_i32 s1, s0, 31
	s_lshl_b64 s[0:1], s[0:1], 12
	v_fma_f32 v75, -v155, v173, 1.0
	v_fmac_f32_e32 v173, v75, v173
	v_div_scale_f32 v75, vcc, v77, v79, v77
	v_mul_f32_e32 v81, v75, v173
	v_fma_f32 v172, -v155, v81, v75
	v_fmac_f32_e32 v81, v172, v173
	v_fma_f32 v75, -v155, v81, v75
	v_div_fmas_f32 v75, v75, v173, v81
	v_div_fixup_f32 v75, v75, v79, v77
	v_mul_f32_e32 v77, v75, v189
	v_mul_f32_e32 v79, v75, v190
	v_lshl_add_u64 v[172:173], v[68:69], 0, s[0:1]
	v_cvt_pk_bf16_f32 v77, v77, v79
	global_store_dword v[172:173], v77, off offset:2048
	v_mul_f32_e32 v77, v75, v187
	v_mul_f32_e32 v79, v75, v188
	v_cvt_pk_bf16_f32 v77, v77, v79
	global_store_dword v[172:173], v77, off offset:2304
	v_mul_f32_e32 v77, v75, v185
	v_mul_f32_e32 v79, v75, v186
	v_cvt_pk_bf16_f32 v77, v77, v79
	global_store_dword v[172:173], v77, off offset:2560
	v_mul_f32_e32 v77, v75, v183
	v_mul_f32_e32 v79, v75, v184
	v_cvt_pk_bf16_f32 v77, v77, v79
	global_store_dword v[172:173], v77, off offset:2816
	v_mul_f32_e32 v77, v75, v181
	v_mul_f32_e32 v79, v75, v182
	v_cvt_pk_bf16_f32 v77, v77, v79
	global_store_dword v[172:173], v77, off offset:3072
	v_mul_f32_e32 v77, v75, v179
	v_mul_f32_e32 v79, v75, v180
	v_cvt_pk_bf16_f32 v77, v77, v79
	global_store_dword v[172:173], v77, off offset:3328
	v_mul_f32_e32 v77, v75, v177
	v_mul_f32_e32 v79, v75, v178
	v_cvt_pk_bf16_f32 v77, v77, v79
	global_store_dword v[172:173], v77, off offset:3584
	v_fmamk_f32 v77, v205, 0x3a800000, v102
	v_mul_f32_e32 v79, 0x4f800000, v77
	v_cmp_gt_f32_e32 vcc, s23, v77
	v_mul_f32_e32 v81, v75, v175
	v_mul_f32_e32 v177, 0x4f800000, v122
	v_cndmask_b32_e32 v77, v77, v79, vcc
	v_sqrt_f32_e32 v79, v77
	v_mul_f32_e32 v75, v75, v176
	v_add_u32_e32 v174, -1, v79
	v_fma_f32 v175, -v174, v79, v77
	v_cmp_ge_f32_e64 s[4:5], 0, v175
	v_add_u32_e32 v175, 1, v79
	s_nop 0
	v_cndmask_b32_e64 v174, v79, v174, s[4:5]
	v_fma_f32 v79, -v175, v79, v77
	v_cmp_lt_f32_e64 s[4:5], 0, v79
	s_nop 1
	v_cndmask_b32_e64 v79, v174, v175, s[4:5]
	v_mul_f32_e32 v174, 0x37800000, v79
	v_cndmask_b32_e32 v79, v79, v174, vcc
	v_cmp_class_f32_e32 vcc, v77, v103
	v_cmp_gt_f32_e64 s[4:5], s23, v122
	v_cvt_pk_bf16_f32 v75, v81, v75
	v_cndmask_b32_e32 v77, v79, v77, vcc
	v_div_scale_f32 v79, s[0:1], v77, v77, 1.0
	v_rcp_f32_e32 v174, v79
	v_cndmask_b32_e64 v122, v122, v177, s[4:5]
	v_sqrt_f32_e32 v177, v122
	global_store_dword v[172:173], v75, off offset:3840
	v_fma_f32 v175, -v79, v174, 1.0
	v_fmac_f32_e32 v174, v175, v174
	v_div_scale_f32 v175, vcc, 1.0, v77, 1.0
	v_mul_f32_e32 v176, v175, v174
	v_fma_f32 v178, -v79, v176, v175
	v_fmac_f32_e32 v176, v178, v174
	v_fma_f32 v79, -v79, v176, v175
	v_add_u32_e32 v175, -1, v177
	v_fma_f32 v178, -v175, v177, v122
	v_cmp_ge_f32_e64 s[6:7], 0, v178
	v_add_u32_e32 v178, 1, v177
	v_div_fmas_f32 v79, v79, v174, v176
	v_cndmask_b32_e64 v175, v177, v175, s[6:7]
	v_fma_f32 v177, -v178, v177, v122
	v_cmp_lt_f32_e64 s[6:7], 0, v177
	v_div_fixup_f32 v77, v79, v77, 1.0
	s_nop 0
	v_cndmask_b32_e64 v175, v175, v178, s[6:7]
	v_mul_f32_e32 v177, 0x37800000, v175
	v_cndmask_b32_e64 v175, v175, v177, s[4:5]
	v_cmp_class_f32_e64 s[4:5], v122, v103
	s_nop 1
	v_cndmask_b32_e64 v122, v175, v122, s[4:5]
	v_div_scale_f32 v175, s[0:1], v122, v122, 1.0
	v_rcp_f32_e32 v177, v175
	s_nop 0
	v_fma_f32 v79, -v175, v177, 1.0
	v_fmac_f32_e32 v177, v79, v177
	v_div_scale_f32 v79, vcc, 1.0, v122, 1.0
	v_mul_f32_e32 v174, v79, v177
	v_fma_f32 v176, -v175, v174, v79
	v_fmac_f32_e32 v174, v176, v177
	v_fma_f32 v79, -v175, v174, v79
	v_div_fmas_f32 v79, v79, v177, v174
	v_div_fixup_f32 v79, v79, v122, 1.0
	v_div_scale_f32 v122, s[0:1], v79, v79, v77
	v_rcp_f32_e32 v174, v122
	s_add_i32 s0, s12, 2
	s_ashr_i32 s1, s0, 31
	s_lshl_b64 s[0:1], s[0:1], 12
	v_fma_f32 v75, -v122, v174, 1.0
	v_fmac_f32_e32 v174, v75, v174
	v_div_scale_f32 v75, vcc, v77, v79, v77
	v_mul_f32_e32 v81, v75, v174
	v_fma_f32 v155, -v122, v81, v75
	v_fmac_f32_e32 v81, v155, v174
	v_fma_f32 v75, -v122, v81, v75
	v_div_fmas_f32 v75, v75, v174, v81
	v_div_fixup_f32 v75, v75, v79, v77
	v_mul_f32_e32 v77, v75, v170
	v_mul_f32_e32 v79, v75, v171
	v_lshl_add_u64 v[172:173], v[68:69], 0, s[0:1]
	v_cvt_pk_bf16_f32 v77, v77, v79
	global_store_dword v[172:173], v77, off offset:2048
	v_mul_f32_e32 v77, v75, v168
	v_mul_f32_e32 v79, v75, v169
	v_cvt_pk_bf16_f32 v77, v77, v79
	global_store_dword v[172:173], v77, off offset:2304
	v_mul_f32_e32 v77, v75, v166
	v_mul_f32_e32 v79, v75, v167
	v_cvt_pk_bf16_f32 v77, v77, v79
	global_store_dword v[172:173], v77, off offset:2560
	v_mul_f32_e32 v77, v75, v164
	v_mul_f32_e32 v79, v75, v165
	v_cvt_pk_bf16_f32 v77, v77, v79
	global_store_dword v[172:173], v77, off offset:2816
	v_mul_f32_e32 v77, v75, v162
	v_mul_f32_e32 v79, v75, v163
	v_cvt_pk_bf16_f32 v77, v77, v79
	global_store_dword v[172:173], v77, off offset:3072
	v_mul_f32_e32 v77, v75, v160
	v_mul_f32_e32 v79, v75, v161
	v_cvt_pk_bf16_f32 v77, v77, v79
	global_store_dword v[172:173], v77, off offset:3328
	v_mul_f32_e32 v77, v75, v158
	v_mul_f32_e32 v79, v75, v159
	v_cvt_pk_bf16_f32 v77, v77, v79
	global_store_dword v[172:173], v77, off offset:3584
	v_mul_f32_e32 v77, 0x4f800000, v31
	v_cmp_gt_f32_e32 vcc, s23, v31
	v_mul_f32_e32 v79, v75, v156
	v_mul_f32_e32 v75, v75, v157
	v_cndmask_b32_e32 v31, v31, v77, vcc
	v_sqrt_f32_e32 v77, v31
	v_mul_f32_e32 v157, 0x4f800000, v108
	v_add_u32_e32 v122, -1, v77
	v_fma_f32 v155, -v122, v77, v31
	v_cmp_ge_f32_e64 s[4:5], 0, v155
	v_add_u32_e32 v155, 1, v77
	s_nop 0
	v_cndmask_b32_e64 v122, v77, v122, s[4:5]
	v_fma_f32 v77, -v155, v77, v31
	v_cmp_lt_f32_e64 s[4:5], 0, v77
	s_nop 1
	v_cndmask_b32_e64 v77, v122, v155, s[4:5]
	v_mul_f32_e32 v122, 0x37800000, v77
	v_cndmask_b32_e32 v77, v77, v122, vcc
	v_cmp_class_f32_e32 vcc, v31, v103
	v_cmp_gt_f32_e64 s[4:5], s23, v108
	v_cvt_pk_bf16_f32 v75, v79, v75
	v_cndmask_b32_e32 v31, v77, v31, vcc
	v_div_scale_f32 v77, s[0:1], v31, v31, 1.0
	v_rcp_f32_e32 v122, v77
	v_cndmask_b32_e64 v108, v108, v157, s[4:5]
	v_sqrt_f32_e32 v157, v108
	global_store_dword v[172:173], v75, off offset:3840
	v_fma_f32 v155, -v77, v122, 1.0
	v_fmac_f32_e32 v122, v155, v122
	v_div_scale_f32 v155, vcc, 1.0, v31, 1.0
	v_mul_f32_e32 v156, v155, v122
	v_fma_f32 v158, -v77, v156, v155
	v_fmac_f32_e32 v156, v158, v122
	v_fma_f32 v77, -v77, v156, v155
	v_add_u32_e32 v155, -1, v157
	v_fma_f32 v158, -v155, v157, v108
	v_cmp_ge_f32_e64 s[6:7], 0, v158
	v_add_u32_e32 v158, 1, v157
	v_div_fmas_f32 v77, v77, v122, v156
	v_cndmask_b32_e64 v155, v157, v155, s[6:7]
	v_fma_f32 v157, -v158, v157, v108
	v_cmp_lt_f32_e64 s[6:7], 0, v157
	v_div_fixup_f32 v31, v77, v31, 1.0
	s_nop 0
	v_cndmask_b32_e64 v155, v155, v158, s[6:7]
	v_mul_f32_e32 v157, 0x37800000, v155
	v_cndmask_b32_e64 v155, v155, v157, s[4:5]
	v_cmp_class_f32_e64 s[4:5], v108, v103
	s_nop 1
	v_cndmask_b32_e64 v108, v155, v108, s[4:5]
	v_div_scale_f32 v155, s[0:1], v108, v108, 1.0
	v_rcp_f32_e32 v157, v155
	s_nop 0
	v_fma_f32 v77, -v155, v157, 1.0
	v_fmac_f32_e32 v157, v77, v157
	v_div_scale_f32 v77, vcc, 1.0, v108, 1.0
	v_mul_f32_e32 v122, v77, v157
	v_fma_f32 v156, -v155, v122, v77
	v_fmac_f32_e32 v122, v156, v157
	v_fma_f32 v77, -v155, v122, v77
	v_div_fmas_f32 v77, v77, v157, v122
	v_div_fixup_f32 v77, v77, v108, 1.0
	v_div_scale_f32 v108, s[0:1], v77, v77, v31
	v_rcp_f32_e32 v122, v108
	s_add_i32 s0, s12, 3
	s_ashr_i32 s1, s0, 31
	s_lshl_b64 s[0:1], s[0:1], 12
	v_fma_f32 v75, -v108, v122, 1.0
	v_fmac_f32_e32 v122, v75, v122
	v_div_scale_f32 v75, vcc, v31, v77, v31
	v_mul_f32_e32 v79, v75, v122
	v_fma_f32 v81, -v108, v79, v75
	v_fmac_f32_e32 v79, v81, v122
	v_fma_f32 v75, -v108, v79, v75
	v_div_fmas_f32 v75, v75, v122, v79
	v_div_fixup_f32 v31, v75, v77, v31
	v_mul_f32_e32 v75, v31, v153
	v_mul_f32_e32 v77, v31, v154
	v_lshl_add_u64 v[156:157], v[68:69], 0, s[0:1]
	v_cvt_pk_bf16_f32 v75, v75, v77
	global_store_dword v[156:157], v75, off offset:2048
	v_mul_f32_e32 v75, v31, v151
	v_mul_f32_e32 v77, v31, v152
	v_cvt_pk_bf16_f32 v75, v75, v77
	global_store_dword v[156:157], v75, off offset:2304
	v_mul_f32_e32 v75, v31, v149
	v_mul_f32_e32 v77, v31, v150
	v_cvt_pk_bf16_f32 v75, v75, v77
	global_store_dword v[156:157], v75, off offset:2560
	v_mul_f32_e32 v75, v31, v147
	v_mul_f32_e32 v77, v31, v148
	v_cvt_pk_bf16_f32 v75, v75, v77
	global_store_dword v[156:157], v75, off offset:2816
	v_mul_f32_e32 v75, v31, v145
	v_mul_f32_e32 v77, v31, v146
	v_cvt_pk_bf16_f32 v75, v75, v77
	global_store_dword v[156:157], v75, off offset:3072
	v_mul_f32_e32 v75, v31, v143
	v_mul_f32_e32 v77, v31, v144
	v_cvt_pk_bf16_f32 v75, v75, v77
	global_store_dword v[156:157], v75, off offset:3328
	v_mul_f32_e32 v75, v31, v141
	v_mul_f32_e32 v77, v31, v142
	v_cvt_pk_bf16_f32 v75, v75, v77
	global_store_dword v[156:157], v75, off offset:3584
	v_mul_f32_e32 v75, 0x4f800000, v27
	v_cmp_gt_f32_e32 vcc, s23, v27
	v_mul_f32_e32 v77, v31, v139
	v_mul_f32_e32 v139, 0x4f800000, v107
	v_cndmask_b32_e32 v27, v27, v75, vcc
	v_sqrt_f32_e32 v75, v27
	v_mul_f32_e32 v31, v31, v140
	v_add_u32_e32 v81, -1, v75
	v_fma_f32 v108, -v81, v75, v27
	v_cmp_ge_f32_e64 s[4:5], 0, v108
	v_add_u32_e32 v108, 1, v75
	s_nop 0
	v_cndmask_b32_e64 v81, v75, v81, s[4:5]
	v_fma_f32 v75, -v108, v75, v27
	v_cmp_lt_f32_e64 s[4:5], 0, v75
	s_nop 1
	v_cndmask_b32_e64 v75, v81, v108, s[4:5]
	v_mul_f32_e32 v81, 0x37800000, v75
	v_cndmask_b32_e32 v75, v75, v81, vcc
	v_cmp_class_f32_e32 vcc, v27, v103
	v_cmp_gt_f32_e64 s[4:5], s23, v107
	v_cvt_pk_bf16_f32 v31, v77, v31
	v_cndmask_b32_e32 v27, v75, v27, vcc
	v_div_scale_f32 v75, s[0:1], v27, v27, 1.0
	v_rcp_f32_e32 v81, v75
	v_cndmask_b32_e64 v107, v107, v139, s[4:5]
	v_sqrt_f32_e32 v139, v107
	global_store_dword v[156:157], v31, off offset:3840
	v_fma_f32 v108, -v75, v81, 1.0
	v_fmac_f32_e32 v81, v108, v81
	v_div_scale_f32 v108, vcc, 1.0, v27, 1.0
	v_mul_f32_e32 v122, v108, v81
	v_fma_f32 v140, -v75, v122, v108
	v_fmac_f32_e32 v122, v140, v81
	v_fma_f32 v75, -v75, v122, v108
	v_add_u32_e32 v108, -1, v139
	v_fma_f32 v140, -v108, v139, v107
	v_cmp_ge_f32_e64 s[6:7], 0, v140
	v_add_u32_e32 v140, 1, v139
	v_div_fmas_f32 v75, v75, v81, v122
	v_cndmask_b32_e64 v108, v139, v108, s[6:7]
	v_fma_f32 v139, -v140, v139, v107
	v_cmp_lt_f32_e64 s[6:7], 0, v139
	v_div_fixup_f32 v27, v75, v27, 1.0
	s_nop 0
	v_cndmask_b32_e64 v108, v108, v140, s[6:7]
	v_mul_f32_e32 v139, 0x37800000, v108
	v_cndmask_b32_e64 v108, v108, v139, s[4:5]
	v_cmp_class_f32_e64 s[4:5], v107, v103
	s_nop 1
	v_cndmask_b32_e64 v107, v108, v107, s[4:5]
	v_div_scale_f32 v108, s[0:1], v107, v107, 1.0
	v_rcp_f32_e32 v139, v108
	s_nop 0
	v_fma_f32 v75, -v108, v139, 1.0
	v_fmac_f32_e32 v139, v75, v139
	v_div_scale_f32 v75, vcc, 1.0, v107, 1.0
	v_mul_f32_e32 v81, v75, v139
	v_fma_f32 v122, -v108, v81, v75
	v_fmac_f32_e32 v81, v122, v139
	v_fma_f32 v75, -v108, v81, v75
	v_div_fmas_f32 v75, v75, v139, v81
	v_div_fixup_f32 v75, v75, v107, 1.0
	v_div_scale_f32 v81, s[0:1], v75, v75, v27
	v_rcp_f32_e32 v107, v81
	s_add_i32 s0, s12, 4
	s_ashr_i32 s1, s0, 31
	s_lshl_b64 s[0:1], s[0:1], 12
	v_fma_f32 v31, -v81, v107, 1.0
	v_fmac_f32_e32 v107, v31, v107
	v_div_scale_f32 v31, vcc, v27, v75, v27
	v_mul_f32_e32 v77, v31, v107
	v_fma_f32 v79, -v81, v77, v31
	v_fmac_f32_e32 v77, v79, v107
	v_fma_f32 v31, -v81, v77, v31
	v_div_fmas_f32 v31, v31, v107, v77
	v_div_fixup_f32 v27, v31, v75, v27
	v_mul_f32_e32 v31, v27, v132
	v_mul_f32_e32 v75, v27, v133
	v_lshl_add_u64 v[140:141], v[68:69], 0, s[0:1]
	v_cvt_pk_bf16_f32 v31, v31, v75
	global_store_dword v[140:141], v31, off offset:2048
	v_mul_f32_e32 v31, v27, v130
	v_mul_f32_e32 v75, v27, v131
	v_cvt_pk_bf16_f32 v31, v31, v75
	global_store_dword v[140:141], v31, off offset:2304
	v_mul_f32_e32 v31, v27, v128
	v_mul_f32_e32 v75, v27, v129
	v_cvt_pk_bf16_f32 v31, v31, v75
	global_store_dword v[140:141], v31, off offset:2560
	v_mul_f32_e32 v31, v27, v126
	v_mul_f32_e32 v75, v27, v127
	v_cvt_pk_bf16_f32 v31, v31, v75
	global_store_dword v[140:141], v31, off offset:2816
	v_mul_f32_e32 v31, v27, v123
	v_mul_f32_e32 v75, v27, v138
	v_cvt_pk_bf16_f32 v31, v31, v75
	global_store_dword v[140:141], v31, off offset:3072
	v_mul_f32_e32 v31, v27, v136
	v_mul_f32_e32 v75, v27, v137
	v_cvt_pk_bf16_f32 v31, v31, v75
	global_store_dword v[140:141], v31, off offset:3328
	v_mul_f32_e32 v31, v27, v134
	v_mul_f32_e32 v75, v27, v135
	v_cvt_pk_bf16_f32 v31, v31, v75
	global_store_dword v[140:141], v31, off offset:3584
	v_mul_f32_e32 v31, 0x4f800000, v23
	v_cmp_gt_f32_e32 vcc, s23, v23
	v_mul_f32_e32 v108, 0x4f800000, v106
	v_mul_f32_e32 v75, v27, v124
	v_cndmask_b32_e32 v23, v23, v31, vcc
	v_sqrt_f32_e32 v31, v23
	v_mul_f32_e32 v27, v27, v125
	v_add_u32_e32 v79, -1, v31
	v_fma_f32 v81, -v79, v31, v23
	v_cmp_ge_f32_e64 s[4:5], 0, v81
	v_add_u32_e32 v81, 1, v31
	s_nop 0
	v_cndmask_b32_e64 v79, v31, v79, s[4:5]
	v_fma_f32 v31, -v81, v31, v23
	v_cmp_lt_f32_e64 s[4:5], 0, v31
	s_nop 1
	v_cndmask_b32_e64 v31, v79, v81, s[4:5]
	v_mul_f32_e32 v79, 0x37800000, v31
	v_cndmask_b32_e32 v31, v31, v79, vcc
	v_cmp_class_f32_e32 vcc, v23, v103
	v_cmp_gt_f32_e64 s[4:5], s23, v106
	v_cvt_pk_bf16_f32 v27, v75, v27
	v_cndmask_b32_e32 v23, v31, v23, vcc
	v_div_scale_f32 v31, s[0:1], v23, v23, 1.0
	v_rcp_f32_e32 v79, v31
	v_cndmask_b32_e64 v106, v106, v108, s[4:5]
	v_sqrt_f32_e32 v108, v106
	global_store_dword v[140:141], v27, off offset:3840
	v_fma_f32 v81, -v31, v79, 1.0
	v_fmac_f32_e32 v79, v81, v79
	v_div_scale_f32 v81, vcc, 1.0, v23, 1.0
	v_mul_f32_e32 v107, v81, v79
	v_fma_f32 v122, -v31, v107, v81
	v_fmac_f32_e32 v107, v122, v79
	v_fma_f32 v31, -v31, v107, v81
	v_add_u32_e32 v81, -1, v108
	v_fma_f32 v122, -v81, v108, v106
	v_cmp_ge_f32_e64 s[6:7], 0, v122
	v_add_u32_e32 v122, 1, v108
	v_div_fmas_f32 v31, v31, v79, v107
	v_cndmask_b32_e64 v81, v108, v81, s[6:7]
	v_fma_f32 v108, -v122, v108, v106
	v_cmp_lt_f32_e64 s[6:7], 0, v108
	v_div_fixup_f32 v23, v31, v23, 1.0
	s_nop 0
	v_cndmask_b32_e64 v81, v81, v122, s[6:7]
	v_mul_f32_e32 v108, 0x37800000, v81
	v_cndmask_b32_e64 v81, v81, v108, s[4:5]
	v_cmp_class_f32_e64 s[4:5], v106, v103
	s_nop 1
	v_cndmask_b32_e64 v81, v81, v106, s[4:5]
	v_div_scale_f32 v106, s[0:1], v81, v81, 1.0
	v_rcp_f32_e32 v108, v106
	s_nop 0
	v_fma_f32 v31, -v106, v108, 1.0
	v_fmac_f32_e32 v108, v31, v108
	v_div_scale_f32 v31, vcc, 1.0, v81, 1.0
	v_mul_f32_e32 v79, v31, v108
	v_fma_f32 v107, -v106, v79, v31
	v_fmac_f32_e32 v79, v107, v108
	v_fma_f32 v31, -v106, v79, v31
	v_div_fmas_f32 v31, v31, v108, v79
	v_div_fixup_f32 v31, v31, v81, 1.0
	v_div_scale_f32 v79, s[0:1], v31, v31, v23
	v_rcp_f32_e32 v81, v79
	s_add_i32 s0, s12, 5
	s_ashr_i32 s1, s0, 31
	s_lshl_b64 s[0:1], s[0:1], 12
	v_fma_f32 v27, -v79, v81, 1.0
	v_fmac_f32_e32 v81, v27, v81
	v_div_scale_f32 v27, vcc, v23, v31, v23
	v_mul_f32_e32 v75, v27, v81
	v_fma_f32 v77, -v79, v75, v27
	v_fmac_f32_e32 v75, v77, v81
	v_fma_f32 v27, -v79, v75, v27
	v_div_fmas_f32 v27, v27, v81, v75
	v_div_fixup_f32 v23, v27, v31, v23
	v_mul_f32_e32 v27, v23, v120
	v_mul_f32_e32 v31, v23, v121
	v_lshl_add_u64 v[106:107], v[68:69], 0, s[0:1]
	v_cvt_pk_bf16_f32 v27, v27, v31
	global_store_dword v[106:107], v27, off offset:2048
	v_mul_f32_e32 v27, v23, v118
	v_mul_f32_e32 v31, v23, v119
	v_cvt_pk_bf16_f32 v27, v27, v31
	global_store_dword v[106:107], v27, off offset:2304
	v_mul_f32_e32 v27, v23, v116
	v_mul_f32_e32 v31, v23, v117
	v_cvt_pk_bf16_f32 v27, v27, v31
	global_store_dword v[106:107], v27, off offset:2560
	v_mul_f32_e32 v27, v23, v114
	v_mul_f32_e32 v31, v23, v115
	v_cvt_pk_bf16_f32 v27, v27, v31
	global_store_dword v[106:107], v27, off offset:2816
	v_mul_f32_e32 v27, v23, v112
	v_mul_f32_e32 v31, v23, v113
	v_cvt_pk_bf16_f32 v27, v27, v31
	global_store_dword v[106:107], v27, off offset:3072
	v_mul_f32_e32 v27, v23, v110
	v_mul_f32_e32 v31, v23, v111
	v_cvt_pk_bf16_f32 v27, v27, v31
	global_store_dword v[106:107], v27, off offset:3328
	v_mul_f32_e32 v27, v23, v80
	v_mul_f32_e32 v31, v23, v109
	v_cvt_pk_bf16_f32 v27, v27, v31
	global_store_dword v[106:107], v27, off offset:3584
	v_mul_f32_e32 v27, 0x4f800000, v19
	v_cmp_gt_f32_e32 vcc, s23, v19
	v_mul_f32_e32 v31, v23, v76
	v_fmamk_f32 v79, v105, 0x3a800000, v102
	v_cndmask_b32_e32 v19, v19, v27, vcc
	v_sqrt_f32_e32 v27, v19
	v_mul_f32_e32 v80, 0x4f800000, v79
	v_mul_f32_e32 v23, v23, v78
	v_add_u32_e32 v76, -1, v27
	v_fma_f32 v77, -v76, v27, v19
	v_cmp_ge_f32_e64 s[4:5], 0, v77
	v_add_u32_e32 v77, 1, v27
	s_nop 0
	v_cndmask_b32_e64 v76, v27, v76, s[4:5]
	v_fma_f32 v27, -v77, v27, v19
	v_cmp_lt_f32_e64 s[4:5], 0, v27
	s_nop 1
	v_cndmask_b32_e64 v27, v76, v77, s[4:5]
	v_mul_f32_e32 v76, 0x37800000, v27
	v_cndmask_b32_e32 v27, v27, v76, vcc
	v_cmp_class_f32_e32 vcc, v19, v103
	v_cmp_gt_f32_e64 s[4:5], s23, v79
	s_nop 0
	v_cndmask_b32_e32 v19, v27, v19, vcc
	v_div_scale_f32 v27, s[0:1], v19, v19, 1.0
	v_rcp_f32_e32 v76, v27
	v_cndmask_b32_e64 v79, v79, v80, s[4:5]
	v_sqrt_f32_e32 v80, v79
	v_cvt_pk_bf16_f32 v23, v31, v23
	v_fma_f32 v77, -v27, v76, 1.0
	v_fmac_f32_e32 v76, v77, v76
	v_div_scale_f32 v77, vcc, 1.0, v19, 1.0
	v_mul_f32_e32 v78, v77, v76
	v_fma_f32 v81, -v27, v78, v77
	v_fmac_f32_e32 v78, v81, v76
	v_fma_f32 v27, -v27, v78, v77
	v_add_u32_e32 v77, -1, v80
	v_fma_f32 v81, -v77, v80, v79
	v_cmp_ge_f32_e64 s[6:7], 0, v81
	v_add_u32_e32 v81, 1, v80
	v_div_fmas_f32 v27, v27, v76, v78
	v_cndmask_b32_e64 v77, v80, v77, s[6:7]
	v_fma_f32 v80, -v81, v80, v79
	v_cmp_lt_f32_e64 s[6:7], 0, v80
	v_div_fixup_f32 v19, v27, v19, 1.0
	global_store_dword v[106:107], v23, off offset:3840
	v_cndmask_b32_e64 v77, v77, v81, s[6:7]
	v_mul_f32_e32 v80, 0x37800000, v77
	v_cndmask_b32_e64 v77, v77, v80, s[4:5]
	v_cmp_class_f32_e64 s[4:5], v79, v103
	s_nop 1
	v_cndmask_b32_e64 v77, v77, v79, s[4:5]
	v_div_scale_f32 v79, s[0:1], v77, v77, 1.0
	v_rcp_f32_e32 v80, v79
	s_nop 0
	v_fma_f32 v27, -v79, v80, 1.0
	v_fmac_f32_e32 v80, v27, v80
	v_div_scale_f32 v27, vcc, 1.0, v77, 1.0
	v_mul_f32_e32 v76, v27, v80
	v_fma_f32 v78, -v79, v76, v27
	v_fmac_f32_e32 v76, v78, v80
	v_fma_f32 v27, -v79, v76, v27
	v_div_fmas_f32 v27, v27, v80, v76
	v_div_fixup_f32 v27, v27, v77, 1.0
	v_div_scale_f32 v76, s[0:1], v27, v27, v19
	v_rcp_f32_e32 v77, v76
	s_add_i32 s0, s12, 6
	s_ashr_i32 s1, s0, 31
	s_lshl_b64 s[0:1], s[0:1], 12
	v_fma_f32 v23, -v76, v77, 1.0
	v_fmac_f32_e32 v77, v23, v77
	v_div_scale_f32 v23, vcc, v19, v27, v19
	v_mul_f32_e32 v31, v23, v77
	v_fma_f32 v75, -v76, v31, v23
	v_fmac_f32_e32 v31, v75, v77
	v_fma_f32 v23, -v76, v31, v23
	v_div_fmas_f32 v23, v23, v77, v31
	v_div_fixup_f32 v19, v23, v27, v19
	v_mul_f32_e32 v23, v19, v73
	v_mul_f32_e32 v27, v19, v74
	v_lshl_add_u64 v[76:77], v[68:69], 0, s[0:1]
	v_cvt_pk_bf16_f32 v23, v23, v27
	global_store_dword v[76:77], v23, off offset:2048
	v_mul_f32_e32 v23, v19, v71
	v_mul_f32_e32 v27, v19, v72
	v_cvt_pk_bf16_f32 v23, v23, v27
	global_store_dword v[76:77], v23, off offset:2304
	v_mul_f32_e32 v23, v19, v30
	v_mul_f32_e32 v27, v19, v70
	v_cvt_pk_bf16_f32 v23, v23, v27
	global_store_dword v[76:77], v23, off offset:2560
	v_mul_f32_e32 v23, v19, v28
	v_mul_f32_e32 v27, v19, v29
	v_cvt_pk_bf16_f32 v23, v23, v27
	global_store_dword v[76:77], v23, off offset:2816
	v_mul_f32_e32 v23, v19, v25
	v_mul_f32_e32 v25, v19, v26
	v_cvt_pk_bf16_f32 v23, v23, v25
	v_mul_f32_e32 v22, v19, v22
	global_store_dword v[76:77], v23, off offset:3072
	v_mul_f32_e32 v23, v19, v24
	v_cvt_pk_bf16_f32 v22, v22, v23
	v_mul_f32_e32 v20, v19, v20
	global_store_dword v[76:77], v22, off offset:3328
	v_mul_f32_e32 v21, v19, v21
	v_cvt_pk_bf16_f32 v20, v20, v21
	global_store_dword v[76:77], v20, off offset:3584
	v_mul_f32_e32 v20, 0x4f800000, v15
	v_cmp_gt_f32_e32 vcc, s23, v15
	v_fmamk_f32 v24, v104, 0x3a800000, v102
	v_mul_f32_e32 v25, 0x4f800000, v24
	v_cndmask_b32_e32 v15, v15, v20, vcc
	v_sqrt_f32_e32 v20, v15
	v_mul_f32_e32 v17, v19, v17
	v_mul_f32_e32 v18, v19, v18
	v_add_u32_e32 v21, -1, v20
	v_fma_f32 v22, -v21, v20, v15
	v_cmp_ge_f32_e64 s[4:5], 0, v22
	v_add_u32_e32 v22, 1, v20
	s_nop 0
	v_cndmask_b32_e64 v21, v20, v21, s[4:5]
	v_fma_f32 v20, -v22, v20, v15
	v_cmp_lt_f32_e64 s[4:5], 0, v20
	s_nop 1
	v_cndmask_b32_e64 v20, v21, v22, s[4:5]
	v_mul_f32_e32 v21, 0x37800000, v20
	v_cndmask_b32_e32 v20, v20, v21, vcc
	v_cmp_class_f32_e32 vcc, v15, v103
	v_cmp_gt_f32_e64 s[4:5], s23, v24
	s_nop 0
	v_cndmask_b32_e32 v15, v20, v15, vcc
	v_div_scale_f32 v20, s[0:1], v15, v15, 1.0
	v_rcp_f32_e32 v21, v20
	v_cndmask_b32_e64 v24, v24, v25, s[4:5]
	v_sqrt_f32_e32 v25, v24
	v_cvt_pk_bf16_f32 v17, v17, v18
	v_fma_f32 v22, -v20, v21, 1.0
	v_fmac_f32_e32 v21, v22, v21
	v_div_scale_f32 v22, vcc, 1.0, v15, 1.0
	v_mul_f32_e32 v23, v22, v21
	v_fma_f32 v26, -v20, v23, v22
	v_fmac_f32_e32 v23, v26, v21
	v_fma_f32 v20, -v20, v23, v22
	v_add_u32_e32 v22, -1, v25
	v_fma_f32 v26, -v22, v25, v24
	v_cmp_ge_f32_e64 s[6:7], 0, v26
	v_add_u32_e32 v26, 1, v25
	v_div_fmas_f32 v20, v20, v21, v23
	v_cndmask_b32_e64 v22, v25, v22, s[6:7]
	v_fma_f32 v25, -v26, v25, v24
	v_cmp_lt_f32_e64 s[6:7], 0, v25
	v_div_fixup_f32 v15, v20, v15, 1.0
	global_store_dword v[76:77], v17, off offset:3840
	v_cndmask_b32_e64 v22, v22, v26, s[6:7]
	v_mul_f32_e32 v25, 0x37800000, v22
	v_cndmask_b32_e64 v22, v22, v25, s[4:5]
	v_cmp_class_f32_e64 s[4:5], v24, v103
	s_nop 1
	v_cndmask_b32_e64 v22, v22, v24, s[4:5]
	v_div_scale_f32 v24, s[0:1], v22, v22, 1.0
	v_rcp_f32_e32 v25, v24
	s_nop 0
	v_fma_f32 v20, -v24, v25, 1.0
	v_fmac_f32_e32 v25, v20, v25
	v_div_scale_f32 v20, vcc, 1.0, v22, 1.0
	v_mul_f32_e32 v21, v20, v25
	v_fma_f32 v23, -v24, v21, v20
	v_fmac_f32_e32 v21, v23, v25
	v_fma_f32 v20, -v24, v21, v20
	v_div_fmas_f32 v20, v20, v25, v21
	v_div_fixup_f32 v20, v20, v22, 1.0
	v_div_scale_f32 v21, s[0:1], v20, v20, v15
	v_rcp_f32_e32 v22, v21
	s_add_i32 s0, s12, 7
	s_ashr_i32 s1, s0, 31
	s_lshl_b64 s[0:1], s[0:1], 12
	v_fma_f32 v17, -v21, v22, 1.0
	v_fmac_f32_e32 v22, v17, v22
	v_div_scale_f32 v17, vcc, v15, v20, v15
	v_mul_f32_e32 v18, v17, v22
	v_fma_f32 v19, -v21, v18, v17
	v_fmac_f32_e32 v18, v19, v22
	v_fma_f32 v17, -v21, v18, v17
	v_div_fmas_f32 v17, v17, v22, v18
	v_div_fixup_f32 v15, v17, v20, v15
	v_mul_f32_e32 v14, v15, v14
	v_mul_f32_e32 v16, v15, v16
	v_lshl_add_u64 v[18:19], v[68:69], 0, s[0:1]
	v_cvt_pk_bf16_f32 v14, v14, v16
	v_mul_f32_e32 v12, v15, v12
	global_store_dword v[18:19], v14, off offset:2048
	v_mul_f32_e32 v13, v15, v13
	v_cvt_pk_bf16_f32 v12, v12, v13
	v_mul_f32_e32 v10, v15, v10
	global_store_dword v[18:19], v12, off offset:2304
	v_mul_f32_e32 v11, v15, v11
	v_cvt_pk_bf16_f32 v10, v10, v11
	v_mul_f32_e32 v8, v15, v8
	global_store_dword v[18:19], v10, off offset:2560
	v_mul_f32_e32 v9, v15, v9
	v_cvt_pk_bf16_f32 v8, v8, v9
	v_mul_f32_e32 v6, v15, v6
	global_store_dword v[18:19], v8, off offset:2816
	v_mul_f32_e32 v7, v15, v7
	v_cvt_pk_bf16_f32 v6, v6, v7
	v_mul_f32_e32 v4, v15, v4
	global_store_dword v[18:19], v6, off offset:3072
	v_mul_f32_e32 v5, v15, v5
	v_cvt_pk_bf16_f32 v4, v4, v5
	v_mul_f32_e32 v2, v15, v2
	global_store_dword v[18:19], v4, off offset:3328
	v_mul_f32_e32 v3, v15, v3
	v_cvt_pk_bf16_f32 v2, v2, v3
	v_mul_f32_e32 v0, v15, v0
	global_store_dword v[18:19], v2, off offset:3584
	v_mul_f32_e32 v1, v15, v1
	v_cvt_pk_bf16_f32 v0, v0, v1
	s_cmpk_lt_i32 s15, 0x100
	global_store_dword v[18:19], v0, off offset:3840
	s_waitcnt vmcnt(63) expcnt(7) lgkmcnt(15)
	s_barrier
	s_cbranch_scc1 .LBB0_474
